# hyena Toeplitz MMA restructured: off-diagonal regions pair row-blocks (a,a+4) in the two column halves, 528 instead of 768 MFMAs per wave per conv, results folded with DPP row_ror:8; S5/hyena channel
# speedup vs baseline: 1.0420x; 1.0198x over previous
.LBB0_155:
	v_lshl_add_u32 v4, s0, 3, v125
	v_ashrrev_i32_e32 v5, 31, v4
	s_waitcnt vmcnt(0)
	v_lshlrev_b64 v[0:1], 13, v[4:5]
	v_lshl_add_u64 v[54:55], s[52:53], 0, v[0:1]
	v_lshlrev_b32_e32 v68, 2, v70
	v_lshl_add_u64 v[44:45], v[54:55], 0, v[68:69]
	global_load_dwordx4 v[0:3], v[44:45], off nt
	s_add_i32 s9, s0, 1
	s_cmp_ge_i32 s9, s6
	s_cselect_b64 s[14:15], -1, 0
	s_ashr_i32 s9, s9, 8
	s_cmp_lg_u32 s9, s7
	s_cselect_b64 s[16:17], -1, 0
	s_or_b64 s[16:17], s[14:15], s[16:17]
	v_lshlrev_b64 v[4:5], 12, v[4:5]
	v_lshl_add_u64 v[128:129], s[34:35], 0, v[4:5]
	s_mov_b64 s[14:15], -1
	s_and_b64 vcc, exec, s[16:17]
	v_lshlrev_b32_e32 v46, 2, v78
	v_lshlrev_b32_e32 v52, 2, v80
	v_lshlrev_b32_e32 v34, 2, v82
	v_lshlrev_b32_e32 v32, 2, v84
	v_lshlrev_b32_e32 v126, 1, v70
	s_cbranch_vccz .LBB0_157
	v_mov_b32_e32 v47, v69
	v_mov_b32_e32 v53, v69
	v_lshl_add_u64 v[4:5], v[54:55], 0, v[46:47]
	global_load_dwordx4 v[28:31], v[44:45], off offset:1024 nt
	global_load_dwordx4 v[24:27], v[44:45], off offset:2048 nt
	global_load_dwordx4 v[20:23], v[44:45], off offset:3072 nt
	v_lshl_add_u64 v[6:7], v[54:55], 0, v[52:53]
	global_load_dwordx4 v[16:19], v[4:5], off nt
	global_load_dwordx4 v[12:15], v[6:7], off nt
	v_mov_b32_e32 v35, v69
	v_mov_b32_e32 v33, v69
	v_lshl_add_u64 v[4:5], v[54:55], 0, v[34:35]
	v_lshl_add_u64 v[6:7], v[54:55], 0, v[32:33]
	global_load_dwordx4 v[8:11], v[4:5], off nt
	s_nop 0
	global_load_dwordx4 v[4:7], v[6:7], off nt
	v_and_b32_e32 v35, 64, v77
	global_load_dwordx4 v[36:39], v[114:115], off
	s_waitcnt vmcnt(8)
	v_mul_f32_e32 v33, v1, v1
	v_xor_b32_e32 v40, 32, v77
	v_add_u32_e32 v35, 64, v35
	v_fmac_f32_e32 v33, v0, v0
	v_cmp_lt_i32_e32 vcc, v40, v35
	v_fmac_f32_e32 v33, v2, v2
	v_fmac_f32_e32 v33, v3, v3
	v_cndmask_b32_e32 v40, v77, v40, vcc
	v_lshlrev_b32_e32 v53, 2, v40
	v_xor_b32_e32 v47, 16, v77
	v_cmp_lt_i32_e32 vcc, v47, v35
	v_mov_b32_e32 v127, v69
	s_add_i32 s7, s0, -1
	s_waitcnt vmcnt(7)
	v_mul_f32_e32 v64, v29, v29
	s_waitcnt vmcnt(6)
	v_mul_f32_e32 v65, v25, v25
	v_fmac_f32_e32 v64, v28, v28
	s_waitcnt vmcnt(5)
	v_mul_f32_e32 v66, v21, v21
	v_fmac_f32_e32 v65, v24, v24
	v_fmac_f32_e32 v64, v30, v30
	s_waitcnt vmcnt(4)
	v_mov_b32_e32 v42, v17
	s_waitcnt vmcnt(3)
	v_mov_b32_e32 v43, v13
	v_fmac_f32_e32 v66, v20, v20
	v_fmac_f32_e32 v65, v26, v26
	v_mov_b32_e32 v40, v16
	v_mov_b32_e32 v41, v12
	v_fmac_f32_e32 v64, v31, v31
	v_pk_mul_f32 v[42:43], v[42:43], v[42:43]
	v_fmac_f32_e32 v66, v22, v22
	v_mov_b32_e32 v48, v18
	v_mov_b32_e32 v49, v14
	s_waitcnt vmcnt(2)
	v_mov_b32_e32 v58, v9
	s_waitcnt vmcnt(1)
	v_mov_b32_e32 v59, v5
	v_fmac_f32_e32 v65, v27, v27
	v_add_f32_e32 v33, v33, v64
	v_pk_fma_f32 v[40:41], v[40:41], v[40:41], v[42:43]
	v_mov_b32_e32 v50, v19
	v_mov_b32_e32 v51, v15
	v_mov_b32_e32 v56, v8
	v_mov_b32_e32 v57, v4
	v_fmac_f32_e32 v66, v23, v23
	v_pk_mul_f32 v[58:59], v[58:59], v[58:59]
	v_add_f32_e32 v33, v33, v65
	v_pk_fma_f32 v[40:41], v[48:49], v[48:49], v[40:41]
	v_mov_b32_e32 v60, v10
	v_mov_b32_e32 v61, v6
	v_pk_fma_f32 v[42:43], v[56:57], v[56:57], v[58:59]
	v_add_f32_e32 v33, v33, v66
	v_pk_fma_f32 v[40:41], v[50:51], v[50:51], v[40:41]
	v_mov_b32_e32 v62, v11
	v_mov_b32_e32 v63, v7
	v_pk_fma_f32 v[42:43], v[60:61], v[60:61], v[42:43]
	v_add_f32_e32 v33, v33, v40
	v_pk_fma_f32 v[42:43], v[62:63], v[62:63], v[42:43]
	v_add_f32_e32 v33, v33, v41
	v_add_f32_e32 v33, v33, v42
	v_add_f32_e32 v33, v33, v43
	ds_bpermute_b32 v40, v53, v33
	v_cndmask_b32_e32 v42, v77, v47, vcc
	v_lshlrev_b32_e32 v42, 2, v42
	v_xor_b32_e32 v41, 8, v77
	v_cmp_lt_i32_e32 vcc, v41, v35
	s_waitcnt lgkmcnt(0)
	v_add_f32_e32 v33, v33, v40
	ds_bpermute_b32 v40, v42, v33
	v_cndmask_b32_e32 v41, v77, v41, vcc
	v_lshlrev_b32_e32 v41, 2, v41
	v_xor_b32_e32 v42, 4, v77
	v_cmp_lt_i32_e32 vcc, v42, v35
	s_waitcnt lgkmcnt(0)
	v_add_f32_e32 v33, v33, v40
	ds_bpermute_b32 v40, v41, v33
	v_cndmask_b32_e32 v42, v77, v42, vcc
	v_lshlrev_b32_e32 v42, 2, v42
	v_xor_b32_e32 v41, 2, v77
	v_cmp_lt_i32_e32 vcc, v41, v35
	s_waitcnt lgkmcnt(0)
	v_add_f32_e32 v33, v33, v40
	ds_bpermute_b32 v40, v42, v33
	v_cndmask_b32_e32 v41, v77, v41, vcc
	v_lshlrev_b32_e32 v41, 2, v41
	v_xor_b32_e32 v42, 1, v77
	v_cmp_lt_i32_e32 vcc, v42, v35
	s_waitcnt lgkmcnt(0)
	v_add_f32_e32 v33, v33, v40
	ds_bpermute_b32 v40, v41, v33
	v_cndmask_b32_e32 v35, v77, v42, vcc
	v_lshlrev_b32_e32 v35, 2, v35
	v_lshl_add_u64 v[64:65], v[128:129], 0, v[126:127]
	s_waitcnt lgkmcnt(0)
	v_add_f32_e32 v33, v33, v40
	ds_bpermute_b32 v35, v35, v33
	ds_read_b128 v[40:43], v73 offset:8192
	ds_read_b128 v[48:51], v73 offset:9216
	ds_read_b128 v[56:59], v73
	ds_read_b128 v[60:63], v73 offset:1024
	s_waitcnt lgkmcnt(3)
	v_pk_add_f32 v[40:41], v[40:41], 1.0 op_sel_hi:[1,0]
	v_pk_add_f32 v[42:43], v[42:43], 1.0 op_sel_hi:[1,0]
	v_add_f32_e32 v33, v33, v35
	v_fmamk_f32 v33, v33, 0x3a000000, v124
	v_mul_f32_e32 v35, 0x4b800000, v33
	v_cmp_gt_f32_e32 vcc, s1, v33
	s_nop 1
	v_cndmask_b32_e32 v33, v33, v35, vcc
	v_rsq_f32_e32 v33, v33
	s_nop 0
	v_mul_f32_e32 v35, 0x45800000, v33
	v_cndmask_b32_e32 v66, v33, v35, vcc
	v_pk_mul_f32 v[130:131], v[0:1], v[66:67] op_sel_hi:[1,0]
	v_pk_mul_f32 v[132:133], v[2:3], v[66:67] op_sel_hi:[1,0]
	s_waitcnt vmcnt(0)
	v_pk_mul_f32 v[36:37], v[36:37], v[130:131]
	v_pk_mul_f32 v[38:39], v[38:39], v[132:133]
	s_waitcnt lgkmcnt(1)
	v_pk_fma_f32 v[36:37], v[40:41], v[36:37], v[56:57]
	v_pk_fma_f32 v[38:39], v[42:43], v[38:39], v[58:59]
	v_cvt_pk_bf16_f32 v36, v36, v37
	v_cvt_pk_bf16_f32 v37, v38, v39
	global_store_dwordx2 v[64:65], v[36:37], off
	v_pk_mul_f32 v[28:29], v[28:29], v[66:67] op_sel_hi:[1, 0]
	v_pk_mul_f32 v[30:31], v[30:31], v[66:67] op_sel_hi:[1, 0]
	v_pk_add_f32 v[40:41], v[48:49], 1.0 op_sel_hi:[1, 0]
	v_pk_add_f32 v[42:43], v[50:51], 1.0 op_sel_hi:[1, 0]
	v_pk_mul_f32 v[24:25], v[24:25], v[66:67] op_sel_hi:[1, 0]
	v_pk_mul_f32 v[26:27], v[26:27], v[66:67] op_sel_hi:[1, 0]
	v_pk_mul_f32 v[20:21], v[20:21], v[66:67] op_sel_hi:[1, 0]
	v_pk_mul_f32 v[22:23], v[22:23], v[66:67] op_sel_hi:[1, 0]
	v_pk_mul_f32 v[16:17], v[16:17], v[66:67] op_sel_hi:[1, 0]
	v_pk_mul_f32 v[18:19], v[18:19], v[66:67] op_sel_hi:[1, 0]
	v_pk_mul_f32 v[12:13], v[12:13], v[66:67] op_sel_hi:[1, 0]
	v_pk_mul_f32 v[14:15], v[14:15], v[66:67] op_sel_hi:[1, 0]
	v_pk_mul_f32 v[8:9], v[8:9], v[66:67] op_sel_hi:[1, 0]
	v_pk_mul_f32 v[10:11], v[10:11], v[66:67] op_sel_hi:[1, 0]
	v_pk_mul_f32 v[4:5], v[4:5], v[66:67] op_sel_hi:[1, 0]
	v_pk_mul_f32 v[6:7], v[6:7], v[66:67] op_sel_hi:[1, 0]
	s_waitcnt vmcnt(1)
	v_pk_mul_f32 v[28:29], v[184:185], v[28:29]
	v_pk_mul_f32 v[30:31], v[186:187], v[30:31]
	s_waitcnt lgkmcnt(0)
	v_pk_fma_f32 v[28:29], v[40:41], v[28:29], v[60:61]
	v_pk_fma_f32 v[30:31], v[42:43], v[30:31], v[62:63]
	v_cvt_pk_bf16_f32 v28, v28, v29
	v_cvt_pk_bf16_f32 v29, v30, v31
	global_store_dwordx2 v[64:65], v[28:29], off offset:512
	ds_read_b128 v[36:39], v73 offset:10240
	ds_read_b128 v[40:43], v73 offset:11264
	ds_read_b128 v[48:51], v73 offset:2048
	ds_read_b128 v[56:59], v73 offset:3072
	s_waitcnt lgkmcnt(3)
	v_pk_add_f32 v[36:37], v[36:37], 1.0 op_sel_hi:[1, 0]
	v_pk_add_f32 v[38:39], v[38:39], 1.0 op_sel_hi:[1, 0]
	s_waitcnt vmcnt(2)
	v_pk_mul_f32 v[24:25], v[188:189], v[24:25]
	v_pk_mul_f32 v[26:27], v[190:191], v[26:27]
	s_waitcnt lgkmcnt(1)
	v_pk_fma_f32 v[24:25], v[36:37], v[24:25], v[48:49]
	v_pk_fma_f32 v[26:27], v[38:39], v[26:27], v[50:51]
	v_cvt_pk_bf16_f32 v24, v24, v25
	v_cvt_pk_bf16_f32 v25, v26, v27
	global_store_dwordx2 v[64:65], v[24:25], off offset:1024
	v_pk_add_f32 v[28:29], v[40:41], 1.0 op_sel_hi:[1, 0]
	v_pk_add_f32 v[30:31], v[42:43], 1.0 op_sel_hi:[1, 0]
	s_waitcnt vmcnt(3)
	v_pk_mul_f32 v[20:21], v[20:21], v[192:193]
	v_pk_mul_f32 v[22:23], v[22:23], v[194:195]
	s_waitcnt lgkmcnt(0)
	v_pk_fma_f32 v[20:21], v[20:21], v[28:29], v[56:57]
	v_pk_fma_f32 v[22:23], v[22:23], v[30:31], v[58:59]
	v_cvt_pk_bf16_f32 v20, v20, v21
	v_cvt_pk_bf16_f32 v21, v22, v23
	global_store_dwordx2 v[64:65], v[20:21], off offset:1536
	ds_read_b128 v[24:27], v73 offset:12288
	ds_read_b128 v[28:31], v73 offset:13312
	ds_read_b128 v[36:39], v73 offset:4096
	ds_read_b128 v[40:43], v73 offset:5120
	s_waitcnt lgkmcnt(3)
	v_pk_add_f32 v[24:25], v[24:25], 1.0 op_sel_hi:[1, 0]
	v_pk_add_f32 v[26:27], v[26:27], 1.0 op_sel_hi:[1, 0]
	s_waitcnt vmcnt(4)
	v_pk_mul_f32 v[16:17], v[16:17], v[196:197]
	v_pk_mul_f32 v[18:19], v[18:19], v[198:199]
	s_waitcnt lgkmcnt(1)
	v_pk_fma_f32 v[16:17], v[16:17], v[24:25], v[36:37]
	v_pk_fma_f32 v[18:19], v[18:19], v[26:27], v[38:39]
	v_cvt_pk_bf16_f32 v16, v16, v17
	v_cvt_pk_bf16_f32 v17, v18, v19
	global_store_dwordx2 v[64:65], v[16:17], off offset:2048
	v_pk_add_f32 v[20:21], v[28:29], 1.0 op_sel_hi:[1, 0]
	v_pk_add_f32 v[22:23], v[30:31], 1.0 op_sel_hi:[1, 0]
	s_waitcnt vmcnt(5)
	v_pk_mul_f32 v[12:13], v[12:13], v[200:201]
	v_pk_mul_f32 v[14:15], v[14:15], v[202:203]
	s_waitcnt lgkmcnt(0)
	v_pk_fma_f32 v[12:13], v[12:13], v[20:21], v[40:41]
	v_pk_fma_f32 v[14:15], v[14:15], v[22:23], v[42:43]
	v_cvt_pk_bf16_f32 v12, v12, v13
	v_cvt_pk_bf16_f32 v13, v14, v15
	global_store_dwordx2 v[64:65], v[12:13], off offset:2560
	ds_read_b128 v[16:19], v73 offset:14336
	ds_read_b128 v[20:23], v73 offset:15360
	ds_read_b128 v[24:27], v73 offset:6144
	ds_read_b128 v[28:31], v73 offset:7168
	s_waitcnt lgkmcnt(3)
	v_pk_add_f32 v[16:17], v[16:17], 1.0 op_sel_hi:[1, 0]
	v_pk_add_f32 v[18:19], v[18:19], 1.0 op_sel_hi:[1, 0]
	s_waitcnt vmcnt(6)
	v_pk_mul_f32 v[8:9], v[8:9], v[204:205]
	v_pk_mul_f32 v[10:11], v[10:11], v[206:207]
	s_waitcnt lgkmcnt(1)
	v_pk_fma_f32 v[8:9], v[8:9], v[16:17], v[24:25]
	v_pk_fma_f32 v[10:11], v[10:11], v[18:19], v[26:27]
	v_cvt_pk_bf16_f32 v8, v8, v9
	v_cvt_pk_bf16_f32 v9, v10, v11
	global_store_dwordx2 v[64:65], v[8:9], off offset:3072
	v_pk_add_f32 v[12:13], v[20:21], 1.0 op_sel_hi:[1, 0]
	v_pk_add_f32 v[14:15], v[22:23], 1.0 op_sel_hi:[1, 0]
	s_waitcnt vmcnt(7)
	v_pk_mul_f32 v[4:5], v[4:5], v[208:209]
	v_pk_mul_f32 v[6:7], v[6:7], v[210:211]
	s_waitcnt lgkmcnt(0)
	v_pk_fma_f32 v[4:5], v[4:5], v[12:13], v[28:29]
	v_pk_fma_f32 v[6:7], v[6:7], v[14:15], v[30:31]
	v_cvt_pk_bf16_f32 v4, v4, v5
	v_cvt_pk_bf16_f32 v5, v6, v7
	global_store_dwordx2 v[64:65], v[4:5], off offset:3584
	s_cbranch_execnz .LBB0_152
	s_branch .LBB0_158

.LBB0_640:
	s_and_b64 vcc, exec, s[6:7]
	s_cbranch_vccz .LBB0_860
	s_and_b64 vcc, exec, s[8:9]
	s_cbranch_vccz .LBB0_643
	s_mul_i32 s0, s3, 7
	s_add_i32 s14, s0, 0xfffffd00
	v_lshlrev_b32_e32 v96, 3, v144
	s_mov_b32 s54, 7
	s_cbranch_execz .LBB0_644
	s_branch .LBB0_760

.LBB0_759:
	s_mov_b32 s14, s3
	s_mov_b32 s54, 1
	s_barrier

.LBB0_812:
	s_or_b64 exec, exec, s[28:29]
	s_lshl_b64 s[12:13], s[34:35], 13
	v_lshl_add_u64 v[52:53], v[138:139], 0, s[12:13]
	v_add_co_u32_e32 v52, vcc, 0x800000, v52
	v_add_u32_e32 v198, v166, v164
	s_nop 0
	v_addc_co_u32_e32 v53, vcc, 0, v53, vcc
	global_load_dwordx4 v[52:55], v[52:53], off
	v_cmp_eq_u32_e64 s[72:73], 0, v164
	s_nop 3
	s_not_b64 s[74:75], s[72:73]
	v_lshrrev_b32_e32 v243, 4, v164
	v_sub_u32_e32 v243, v166, v243
	v_add_u32_e32 v242, 128, v188
	ds_read_b128 v[60:63], v242 offset:0
	ds_read_b128 v[64:67], v242 offset:32
	ds_read_b128 v[68:71], v242 offset:64
	ds_read_b128 v[72:75], v242 offset:96
	ds_read_b128 v[76:79], v243
	ds_read_b128 v[88:91], v243 offset:64
	v_add_u32_e32 v242, 0xffffff00, v242
	v_mov_b32_e32 v84, 0
	v_mov_b32_e32 v85, 0
	v_mov_b32_e32 v86, 0
	v_mov_b32_e32 v87, 0
	v_mov_b32_e32 v124, 0
	v_mov_b32_e32 v125, 0
	v_mov_b32_e32 v126, 0
	v_mov_b32_e32 v127, 0
	v_mov_b32_e32 v234, 0
	v_mov_b32_e32 v235, 0
	v_mov_b32_e32 v236, 0
	v_mov_b32_e32 v237, 0
	v_mov_b32_e32 v238, 0
	v_mov_b32_e32 v239, 0
	v_mov_b32_e32 v240, 0
	v_mov_b32_e32 v241, 0
	s_mov_b32 s82, 0
	s_waitcnt lgkmcnt(0)
.Lhy1L_loop:
	s_cmp_eq_u32 s82, 0
	s_cselect_b64 s[78:79], s[72:73], -1
	s_cmp_eq_u32 s82, 8
	s_cselect_b64 s[78:79], s[74:75], s[78:79]
	ds_read_b128 v[104:107], v243 offset:128
	s_waitcnt lgkmcnt(6)
	v_cndmask_b32_e64 v76, 0, v76, s[78:79]
	v_cndmask_b32_e64 v77, 0, v77, s[78:79]
	v_cndmask_b32_e64 v78, 0, v78, s[78:79]
	v_cndmask_b32_e64 v79, 0, v79, s[78:79]
	s_nop 1
	v_mfma_f32_16x16x32_bf16 v[238:241], v[72:75], v[76:79], v[238:241]
	v_mfma_f32_16x16x32_bf16 v[234:237], v[68:71], v[76:79], v[234:237]
	ds_read_b128 v[68:71], v242 offset:192
	ds_read_b128 v[72:75], v242 offset:224
	s_waitcnt lgkmcnt(3)
	v_mfma_f32_16x16x32_bf16 v[124:127], v[64:67], v[76:79], v[124:127]
	v_mfma_f32_16x16x32_bf16 v[84:87], v[60:63], v[76:79], v[84:87]
	ds_read_b128 v[120:123], v243 offset:192
	s_waitcnt lgkmcnt(6)
	v_cndmask_b32_e64 v88, 0, v88, s[78:79]
	v_cndmask_b32_e64 v89, 0, v89, s[78:79]
	v_cndmask_b32_e64 v90, 0, v90, s[78:79]
	v_cndmask_b32_e64 v91, 0, v91, s[78:79]
	s_nop 1
	v_mfma_f32_16x16x32_bf16 v[238:241], v[64:67], v[88:91], v[238:241]
	v_mfma_f32_16x16x32_bf16 v[234:237], v[60:63], v[88:91], v[234:237]
	ds_read_b128 v[60:63], v242 offset:128
	ds_read_b128 v[64:67], v242 offset:160
	s_waitcnt lgkmcnt(3)
	v_mfma_f32_16x16x32_bf16 v[124:127], v[72:75], v[88:91], v[124:127]
	v_mfma_f32_16x16x32_bf16 v[84:87], v[68:71], v[88:91], v[84:87]
	s_cmp_eq_u32 s82, 8
	s_cbranch_scc1 .Lhy1L_done
	ds_read_b128 v[76:79], v243 offset:256
	s_waitcnt lgkmcnt(6)
	v_mfma_f32_16x16x32_bf16 v[238:241], v[72:75], v[104:107], v[238:241]
	v_mfma_f32_16x16x32_bf16 v[234:237], v[68:71], v[104:107], v[234:237]
	ds_read_b128 v[68:71], v242 offset:64
	ds_read_b128 v[72:75], v242 offset:96
	s_waitcnt lgkmcnt(3)
	v_mfma_f32_16x16x32_bf16 v[124:127], v[64:67], v[104:107], v[124:127]
	v_mfma_f32_16x16x32_bf16 v[84:87], v[60:63], v[104:107], v[84:87]
	ds_read_b128 v[88:91], v243 offset:320
	s_waitcnt lgkmcnt(6)
	v_mfma_f32_16x16x32_bf16 v[238:241], v[64:67], v[120:123], v[238:241]
	v_mfma_f32_16x16x32_bf16 v[234:237], v[60:63], v[120:123], v[234:237]
	ds_read_b128 v[60:63], v242 offset:0
	ds_read_b128 v[64:67], v242 offset:32
	s_waitcnt lgkmcnt(3)
	v_mfma_f32_16x16x32_bf16 v[124:127], v[72:75], v[120:123], v[124:127]
	v_mfma_f32_16x16x32_bf16 v[84:87], v[68:71], v[120:123], v[84:87]
	v_add_u32_e32 v242, 0xffffff00, v242
	v_add_u32_e32 v243, 0x100, v243
	s_add_i32 s82, s82, 1
	s_branch .Lhy1L_loop
.Lhy1L_done:
	s_waitcnt lgkmcnt(0)
	s_nop 7
	s_nop 1
	v_cndmask_b32_e64 v244, 0, v84, s[74:75]
	v_cndmask_b32_e64 v245, 0, v85, s[74:75]
	v_cndmask_b32_e64 v246, 0, v86, s[74:75]
	v_cndmask_b32_e64 v247, 0, v87, s[74:75]
	v_cndmask_b32_e64 v112, 0, v84, s[72:73]
	v_cndmask_b32_e64 v113, 0, v85, s[72:73]
	v_cndmask_b32_e64 v114, 0, v86, s[72:73]
	v_cndmask_b32_e64 v115, 0, v87, s[72:73]
	v_mov_b32_dpp v116, v244 row_ror:8 row_mask:0xf bank_mask:0xf
	v_mov_b32_dpp v117, v245 row_ror:8 row_mask:0xf bank_mask:0xf
	v_mov_b32_dpp v118, v246 row_ror:8 row_mask:0xf bank_mask:0xf
	v_mov_b32_dpp v119, v247 row_ror:8 row_mask:0xf bank_mask:0xf
	v_cndmask_b32_e64 v244, 0, v124, s[74:75]
	v_cndmask_b32_e64 v245, 0, v125, s[74:75]
	v_cndmask_b32_e64 v246, 0, v126, s[74:75]
	v_cndmask_b32_e64 v247, 0, v127, s[74:75]
	v_cndmask_b32_e64 v92, 0, v124, s[72:73]
	v_cndmask_b32_e64 v93, 0, v125, s[72:73]
	v_cndmask_b32_e64 v94, 0, v126, s[72:73]
	v_cndmask_b32_e64 v95, 0, v127, s[72:73]
	v_mov_b32_dpp v100, v244 row_ror:8 row_mask:0xf bank_mask:0xf
	v_mov_b32_dpp v101, v245 row_ror:8 row_mask:0xf bank_mask:0xf
	v_mov_b32_dpp v102, v246 row_ror:8 row_mask:0xf bank_mask:0xf
	v_mov_b32_dpp v103, v247 row_ror:8 row_mask:0xf bank_mask:0xf
	v_cndmask_b32_e64 v244, 0, v234, s[74:75]
	v_cndmask_b32_e64 v245, 0, v235, s[74:75]
	v_cndmask_b32_e64 v246, 0, v236, s[74:75]
	v_cndmask_b32_e64 v247, 0, v237, s[74:75]
	v_cndmask_b32_e64 v80, 0, v234, s[72:73]
	v_cndmask_b32_e64 v81, 0, v235, s[72:73]
	v_cndmask_b32_e64 v82, 0, v236, s[72:73]
	v_cndmask_b32_e64 v83, 0, v237, s[72:73]
	v_mov_b32_dpp v96, v244 row_ror:8 row_mask:0xf bank_mask:0xf
	v_mov_b32_dpp v97, v245 row_ror:8 row_mask:0xf bank_mask:0xf
	v_mov_b32_dpp v98, v246 row_ror:8 row_mask:0xf bank_mask:0xf
	v_mov_b32_dpp v99, v247 row_ror:8 row_mask:0xf bank_mask:0xf
	v_cndmask_b32_e64 v244, 0, v238, s[74:75]
	v_cndmask_b32_e64 v245, 0, v239, s[74:75]
	v_cndmask_b32_e64 v246, 0, v240, s[74:75]
	v_cndmask_b32_e64 v247, 0, v241, s[74:75]
	v_cndmask_b32_e64 v56, 0, v238, s[72:73]
	v_cndmask_b32_e64 v57, 0, v239, s[72:73]
	v_cndmask_b32_e64 v58, 0, v240, s[72:73]
	v_cndmask_b32_e64 v59, 0, v241, s[72:73]
	v_mov_b32_dpp v108, v244 row_ror:8 row_mask:0xf bank_mask:0xf
	v_mov_b32_dpp v109, v245 row_ror:8 row_mask:0xf bank_mask:0xf
	v_mov_b32_dpp v110, v246 row_ror:8 row_mask:0xf bank_mask:0xf
	v_mov_b32_dpp v111, v247 row_ror:8 row_mask:0xf bank_mask:0xf
	v_add_u32_e32 v242, 0xfffff800, v188
	ds_read_b128 v[60:63], v242
	ds_read_b128 v[64:67], v242 offset:32
	ds_read_b128 v[88:91], v242 offset:64
	ds_read_b128 v[68:71], v242 offset:96
	ds_read_b128 v[104:107], v242 offset:128
	ds_read_b128 v[72:75], v242 offset:160
	ds_read_b128 v[120:123], v242 offset:192
	ds_read_b128 v[76:79], v242 offset:224
	v_add_u32_e32 v243, 0x800, v164
	v_and_b32_e32 v243, 0xfff, v243
	v_add_u32_e32 v243, v166, v243
	ds_read_b128 v[84:87], v243
	s_movk_i32 s2, 0x800
	s_mov_b32 s12, 35
	s_mov_b32 s13, 8
	v_add_u32_e32 v131, 0xfffff800, v135
	s_branch .LBB0_814
.Lhy1H_entry:
	v_cmp_eq_u32_e64 s[72:73], 0, v164
	s_nop 3
	s_not_b64 s[74:75], s[72:73]
	v_lshrrev_b32_e32 v243, 4, v164
	v_sub_u32_e32 v243, v166, v243
	v_add_u32_e32 v243, 0x800, v243
	v_add_u32_e32 v242, -3968, v188
	ds_read_b128 v[60:63], v242 offset:0
	ds_read_b128 v[64:67], v242 offset:32
	ds_read_b128 v[68:71], v242 offset:64
	ds_read_b128 v[72:75], v242 offset:96
	ds_read_b128 v[76:79], v243
	ds_read_b128 v[88:91], v243 offset:64
	v_add_u32_e32 v242, 0xffffff00, v242
	v_mov_b32_e32 v84, 0
	v_mov_b32_e32 v85, 0
	v_mov_b32_e32 v86, 0
	v_mov_b32_e32 v87, 0
	v_mov_b32_e32 v124, 0
	v_mov_b32_e32 v125, 0
	v_mov_b32_e32 v126, 0
	v_mov_b32_e32 v127, 0
	v_mov_b32_e32 v234, 0
	v_mov_b32_e32 v235, 0
	v_mov_b32_e32 v236, 0
	v_mov_b32_e32 v237, 0
	v_mov_b32_e32 v238, 0
	v_mov_b32_e32 v239, 0
	v_mov_b32_e32 v240, 0
	v_mov_b32_e32 v241, 0
	s_mov_b32 s82, 0
	s_waitcnt lgkmcnt(0)

.Lhy1H_done:
	s_waitcnt lgkmcnt(0)
	s_nop 7
	s_nop 1
	v_cndmask_b32_e64 v244, 0, v84, s[74:75]
	v_cndmask_b32_e64 v245, 0, v85, s[74:75]
	v_cndmask_b32_e64 v246, 0, v86, s[74:75]
	v_cndmask_b32_e64 v247, 0, v87, s[74:75]
	v_cndmask_b32_e64 v84, 0, v84, s[72:73]
	v_cndmask_b32_e64 v85, 0, v85, s[72:73]
	v_cndmask_b32_e64 v86, 0, v86, s[72:73]
	v_cndmask_b32_e64 v87, 0, v87, s[72:73]
	v_add_f32_e32 v116, v116, v244
	v_add_f32_e32 v117, v117, v245
	v_add_f32_e32 v118, v118, v246
	v_add_f32_e32 v119, v119, v247
	v_add_f32_dpp v112, v84, v112 row_ror:8 row_mask:0xf bank_mask:0xf
	v_add_f32_dpp v113, v85, v113 row_ror:8 row_mask:0xf bank_mask:0xf
	v_add_f32_dpp v114, v86, v114 row_ror:8 row_mask:0xf bank_mask:0xf
	v_add_f32_dpp v115, v87, v115 row_ror:8 row_mask:0xf bank_mask:0xf
	v_cndmask_b32_e64 v244, 0, v124, s[74:75]
	v_cndmask_b32_e64 v245, 0, v125, s[74:75]
	v_cndmask_b32_e64 v246, 0, v126, s[74:75]
	v_cndmask_b32_e64 v247, 0, v127, s[74:75]
	v_cndmask_b32_e64 v124, 0, v124, s[72:73]
	v_cndmask_b32_e64 v125, 0, v125, s[72:73]
	v_cndmask_b32_e64 v126, 0, v126, s[72:73]
	v_cndmask_b32_e64 v127, 0, v127, s[72:73]
	v_add_f32_e32 v100, v100, v244
	v_add_f32_e32 v101, v101, v245
	v_add_f32_e32 v102, v102, v246
	v_add_f32_e32 v103, v103, v247
	v_add_f32_dpp v92, v124, v92 row_ror:8 row_mask:0xf bank_mask:0xf
	v_add_f32_dpp v93, v125, v93 row_ror:8 row_mask:0xf bank_mask:0xf
	v_add_f32_dpp v94, v126, v94 row_ror:8 row_mask:0xf bank_mask:0xf
	v_add_f32_dpp v95, v127, v95 row_ror:8 row_mask:0xf bank_mask:0xf
	v_cndmask_b32_e64 v244, 0, v234, s[74:75]
	v_cndmask_b32_e64 v245, 0, v235, s[74:75]
	v_cndmask_b32_e64 v246, 0, v236, s[74:75]
	v_cndmask_b32_e64 v247, 0, v237, s[74:75]
	v_cndmask_b32_e64 v234, 0, v234, s[72:73]
	v_cndmask_b32_e64 v235, 0, v235, s[72:73]
	v_cndmask_b32_e64 v236, 0, v236, s[72:73]
	v_cndmask_b32_e64 v237, 0, v237, s[72:73]
	v_add_f32_e32 v96, v96, v244
	v_add_f32_e32 v97, v97, v245
	v_add_f32_e32 v98, v98, v246
	v_add_f32_e32 v99, v99, v247
	v_add_f32_dpp v80, v234, v80 row_ror:8 row_mask:0xf bank_mask:0xf
	v_add_f32_dpp v81, v235, v81 row_ror:8 row_mask:0xf bank_mask:0xf
	v_add_f32_dpp v82, v236, v82 row_ror:8 row_mask:0xf bank_mask:0xf
	v_add_f32_dpp v83, v237, v83 row_ror:8 row_mask:0xf bank_mask:0xf
	v_cndmask_b32_e64 v244, 0, v238, s[74:75]
	v_cndmask_b32_e64 v245, 0, v239, s[74:75]
	v_cndmask_b32_e64 v246, 0, v240, s[74:75]
	v_cndmask_b32_e64 v247, 0, v241, s[74:75]
	v_cndmask_b32_e64 v238, 0, v238, s[72:73]
	v_cndmask_b32_e64 v239, 0, v239, s[72:73]
	v_cndmask_b32_e64 v240, 0, v240, s[72:73]
	v_cndmask_b32_e64 v241, 0, v241, s[72:73]
	v_add_f32_e32 v108, v108, v244
	v_add_f32_e32 v109, v109, v245
	v_add_f32_e32 v110, v110, v246
	v_add_f32_e32 v111, v111, v247
	v_add_f32_dpp v56, v238, v56 row_ror:8 row_mask:0xf bank_mask:0xf
	v_add_f32_dpp v57, v239, v57 row_ror:8 row_mask:0xf bank_mask:0xf
	v_add_f32_dpp v58, v240, v58 row_ror:8 row_mask:0xf bank_mask:0xf
	v_add_f32_dpp v59, v241, v59 row_ror:8 row_mask:0xf bank_mask:0xf
	s_branch .LBB0_818
.LBB0_813:
	v_mfma_f32_16x16x32_bf16 v[92:95], v[76:79], v[124:127], v[92:95]
	s_add_i32 s13, s13, 1
	s_addk_i32 s2, 0x100
	s_add_i32 s12, s12, 4
	v_mfma_f32_16x16x32_bf16 v[112:115], v[120:123], v[124:127], v[112:115]
	v_add_u32_e32 v131, 0xffffff00, v131
	s_cmpk_lg_i32 s2, 0x1000
	v_mfma_f32_16x16x32_bf16 v[108:111], v[72:75], v[124:127], v[108:111]
	v_mfma_f32_16x16x32_bf16 v[96:99], v[104:107], v[124:127], v[96:99]
	s_waitcnt lgkmcnt(1)
	v_mfma_f32_16x16x32_bf16 v[100:103], v[68:71], v[124:127], v[100:103]
	v_mfma_f32_16x16x32_bf16 v[116:119], v[88:91], v[124:127], v[116:119]
	s_cbranch_scc0 .Lhy1H_entry

.LBB0_854:
	v_cmp_eq_u32_e64 s[72:73], 0, v164
	s_nop 3
	s_not_b64 s[74:75], s[72:73]
	v_lshrrev_b32_e32 v243, 4, v164
	v_sub_u32_e32 v243, v166, v243
	v_add_u32_e32 v242, 128, v188
	ds_read_b128 v[40:43], v242 offset:0
	ds_read_b128 v[44:47], v242 offset:32
	ds_read_b128 v[48:51], v242 offset:64
	ds_read_b128 v[52:55], v242 offset:96
	ds_read_b128 v[56:59], v243
	ds_read_b128 v[68:71], v243 offset:64
	v_add_u32_e32 v242, 0xffffff00, v242
	v_mov_b32_e32 v64, 0
	v_mov_b32_e32 v65, 0
	v_mov_b32_e32 v66, 0
	v_mov_b32_e32 v67, 0
	v_mov_b32_e32 v104, 0
	v_mov_b32_e32 v105, 0
	v_mov_b32_e32 v106, 0
	v_mov_b32_e32 v107, 0
	v_mov_b32_e32 v234, 0
	v_mov_b32_e32 v235, 0
	v_mov_b32_e32 v236, 0
	v_mov_b32_e32 v237, 0
	v_mov_b32_e32 v238, 0
	v_mov_b32_e32 v239, 0
	v_mov_b32_e32 v240, 0
	v_mov_b32_e32 v241, 0
	s_mov_b32 s82, 0
	s_waitcnt lgkmcnt(0)
.Lhy2L_loop:
	s_cmp_eq_u32 s82, 0
	s_cselect_b64 s[78:79], s[72:73], -1
	s_cmp_eq_u32 s82, 8
	s_cselect_b64 s[78:79], s[74:75], s[78:79]
	ds_read_b128 v[76:79], v243 offset:128
	s_waitcnt lgkmcnt(6)
	v_cndmask_b32_e64 v56, 0, v56, s[78:79]
	v_cndmask_b32_e64 v57, 0, v57, s[78:79]
	v_cndmask_b32_e64 v58, 0, v58, s[78:79]
	v_cndmask_b32_e64 v59, 0, v59, s[78:79]
	s_nop 1
	v_mfma_f32_16x16x32_bf16 v[238:241], v[52:55], v[56:59], v[238:241]
	v_mfma_f32_16x16x32_bf16 v[234:237], v[48:51], v[56:59], v[234:237]
	ds_read_b128 v[48:51], v242 offset:192
	ds_read_b128 v[52:55], v242 offset:224
	s_waitcnt lgkmcnt(3)
	v_mfma_f32_16x16x32_bf16 v[104:107], v[44:47], v[56:59], v[104:107]
	v_mfma_f32_16x16x32_bf16 v[64:67], v[40:43], v[56:59], v[64:67]
	ds_read_b128 v[92:95], v243 offset:192
	s_waitcnt lgkmcnt(6)
	v_cndmask_b32_e64 v68, 0, v68, s[78:79]
	v_cndmask_b32_e64 v69, 0, v69, s[78:79]
	v_cndmask_b32_e64 v70, 0, v70, s[78:79]
	v_cndmask_b32_e64 v71, 0, v71, s[78:79]
	s_nop 1
	v_mfma_f32_16x16x32_bf16 v[238:241], v[44:47], v[68:71], v[238:241]
	v_mfma_f32_16x16x32_bf16 v[234:237], v[40:43], v[68:71], v[234:237]
	ds_read_b128 v[40:43], v242 offset:128
	ds_read_b128 v[44:47], v242 offset:160
	s_waitcnt lgkmcnt(3)
	v_mfma_f32_16x16x32_bf16 v[104:107], v[52:55], v[68:71], v[104:107]
	v_mfma_f32_16x16x32_bf16 v[64:67], v[48:51], v[68:71], v[64:67]
	s_cmp_eq_u32 s82, 8
	s_cbranch_scc1 .Lhy2L_done
	ds_read_b128 v[56:59], v243 offset:256
	s_waitcnt lgkmcnt(6)
	v_mfma_f32_16x16x32_bf16 v[238:241], v[52:55], v[76:79], v[238:241]
	v_mfma_f32_16x16x32_bf16 v[234:237], v[48:51], v[76:79], v[234:237]
	ds_read_b128 v[48:51], v242 offset:64
	ds_read_b128 v[52:55], v242 offset:96
	s_waitcnt lgkmcnt(3)
	v_mfma_f32_16x16x32_bf16 v[104:107], v[44:47], v[76:79], v[104:107]
	v_mfma_f32_16x16x32_bf16 v[64:67], v[40:43], v[76:79], v[64:67]
	ds_read_b128 v[68:71], v243 offset:320
	s_waitcnt lgkmcnt(6)
	v_mfma_f32_16x16x32_bf16 v[238:241], v[44:47], v[92:95], v[238:241]
	v_mfma_f32_16x16x32_bf16 v[234:237], v[40:43], v[92:95], v[234:237]
	ds_read_b128 v[40:43], v242 offset:0
	ds_read_b128 v[44:47], v242 offset:32
	s_waitcnt lgkmcnt(3)
	v_mfma_f32_16x16x32_bf16 v[104:107], v[52:55], v[92:95], v[104:107]
	v_mfma_f32_16x16x32_bf16 v[64:67], v[48:51], v[92:95], v[64:67]
	v_add_u32_e32 v242, 0xffffff00, v242
	v_add_u32_e32 v243, 0x100, v243
	s_add_i32 s82, s82, 1
	s_branch .Lhy2L_loop
.Lhy2L_done:
	s_waitcnt lgkmcnt(0)
	s_nop 7
	s_nop 1
	v_cndmask_b32_e64 v244, 0, v64, s[74:75]
	v_cndmask_b32_e64 v245, 0, v65, s[74:75]
	v_cndmask_b32_e64 v246, 0, v66, s[74:75]
	v_cndmask_b32_e64 v247, 0, v67, s[74:75]
	v_cndmask_b32_e64 v80, 0, v64, s[72:73]
	v_cndmask_b32_e64 v81, 0, v65, s[72:73]
	v_cndmask_b32_e64 v82, 0, v66, s[72:73]
	v_cndmask_b32_e64 v83, 0, v67, s[72:73]
	v_mov_b32_dpp v100, v244 row_ror:8 row_mask:0xf bank_mask:0xf
	v_mov_b32_dpp v101, v245 row_ror:8 row_mask:0xf bank_mask:0xf
	v_mov_b32_dpp v102, v246 row_ror:8 row_mask:0xf bank_mask:0xf
	v_mov_b32_dpp v103, v247 row_ror:8 row_mask:0xf bank_mask:0xf
	v_cndmask_b32_e64 v244, 0, v104, s[74:75]
	v_cndmask_b32_e64 v245, 0, v105, s[74:75]
	v_cndmask_b32_e64 v246, 0, v106, s[74:75]
	v_cndmask_b32_e64 v247, 0, v107, s[74:75]
	v_cndmask_b32_e64 v72, 0, v104, s[72:73]
	v_cndmask_b32_e64 v73, 0, v105, s[72:73]
	v_cndmask_b32_e64 v74, 0, v106, s[72:73]
	v_cndmask_b32_e64 v75, 0, v107, s[72:73]
	v_mov_b32_dpp v96, v244 row_ror:8 row_mask:0xf bank_mask:0xf
	v_mov_b32_dpp v97, v245 row_ror:8 row_mask:0xf bank_mask:0xf
	v_mov_b32_dpp v98, v246 row_ror:8 row_mask:0xf bank_mask:0xf
	v_mov_b32_dpp v99, v247 row_ror:8 row_mask:0xf bank_mask:0xf
	v_cndmask_b32_e64 v244, 0, v234, s[74:75]
	v_cndmask_b32_e64 v245, 0, v235, s[74:75]
	v_cndmask_b32_e64 v246, 0, v236, s[74:75]
	v_cndmask_b32_e64 v247, 0, v237, s[74:75]
	v_cndmask_b32_e64 v60, 0, v234, s[72:73]
	v_cndmask_b32_e64 v61, 0, v235, s[72:73]
	v_cndmask_b32_e64 v62, 0, v236, s[72:73]
	v_cndmask_b32_e64 v63, 0, v237, s[72:73]
	v_mov_b32_dpp v88, v244 row_ror:8 row_mask:0xf bank_mask:0xf
	v_mov_b32_dpp v89, v245 row_ror:8 row_mask:0xf bank_mask:0xf
	v_mov_b32_dpp v90, v246 row_ror:8 row_mask:0xf bank_mask:0xf
	v_mov_b32_dpp v91, v247 row_ror:8 row_mask:0xf bank_mask:0xf
	v_cndmask_b32_e64 v244, 0, v238, s[74:75]
	v_cndmask_b32_e64 v245, 0, v239, s[74:75]
	v_cndmask_b32_e64 v246, 0, v240, s[74:75]
	v_cndmask_b32_e64 v247, 0, v241, s[74:75]
	v_cndmask_b32_e64 v36, 0, v238, s[72:73]
	v_cndmask_b32_e64 v37, 0, v239, s[72:73]
	v_cndmask_b32_e64 v38, 0, v240, s[72:73]
	v_cndmask_b32_e64 v39, 0, v241, s[72:73]
	v_mov_b32_dpp v84, v244 row_ror:8 row_mask:0xf bank_mask:0xf
	v_mov_b32_dpp v85, v245 row_ror:8 row_mask:0xf bank_mask:0xf
	v_mov_b32_dpp v86, v246 row_ror:8 row_mask:0xf bank_mask:0xf
	v_mov_b32_dpp v87, v247 row_ror:8 row_mask:0xf bank_mask:0xf
	v_add_u32_e32 v242, 0xfffff800, v188
	ds_read_b128 v[40:43], v242
	ds_read_b128 v[44:47], v242 offset:32
	ds_read_b128 v[68:71], v242 offset:64
	ds_read_b128 v[48:51], v242 offset:96
	ds_read_b128 v[76:79], v242 offset:128
	ds_read_b128 v[52:55], v242 offset:160
	ds_read_b128 v[92:95], v242 offset:192
	ds_read_b128 v[56:59], v242 offset:224
	v_add_u32_e32 v243, 0x800, v164
	v_and_b32_e32 v243, 0xfff, v243
	v_add_u32_e32 v243, v166, v243
	ds_read_b128 v[64:67], v243
	s_movk_i32 s2, 0x800
	s_mov_b32 s12, 35
	s_mov_b32 s13, 8
	v_add_u32_e32 v108, 0xfffff800, v135
	s_branch .LBB0_856
.Lhy2H_entry:
	v_cmp_eq_u32_e64 s[72:73], 0, v164
	s_nop 3
	s_not_b64 s[74:75], s[72:73]
	v_lshrrev_b32_e32 v243, 4, v164
	v_sub_u32_e32 v243, v166, v243
	v_add_u32_e32 v243, 0x800, v243
	v_add_u32_e32 v242, -3968, v188
	ds_read_b128 v[40:43], v242 offset:0
	ds_read_b128 v[44:47], v242 offset:32
	ds_read_b128 v[48:51], v242 offset:64
	ds_read_b128 v[52:55], v242 offset:96
	ds_read_b128 v[56:59], v243
	ds_read_b128 v[68:71], v243 offset:64
	v_add_u32_e32 v242, 0xffffff00, v242
	v_mov_b32_e32 v64, 0
	v_mov_b32_e32 v65, 0
	v_mov_b32_e32 v66, 0
	v_mov_b32_e32 v67, 0
	v_mov_b32_e32 v104, 0
	v_mov_b32_e32 v105, 0
	v_mov_b32_e32 v106, 0
	v_mov_b32_e32 v107, 0
	v_mov_b32_e32 v234, 0
	v_mov_b32_e32 v235, 0
	v_mov_b32_e32 v236, 0
	v_mov_b32_e32 v237, 0
	v_mov_b32_e32 v238, 0
	v_mov_b32_e32 v239, 0
	v_mov_b32_e32 v240, 0
	v_mov_b32_e32 v241, 0
	s_mov_b32 s82, 0
	s_waitcnt lgkmcnt(0)

.Lhy2H_done:
	s_waitcnt lgkmcnt(0)
	s_nop 7
	s_nop 1
	v_cndmask_b32_e64 v244, 0, v64, s[74:75]
	v_cndmask_b32_e64 v245, 0, v65, s[74:75]
	v_cndmask_b32_e64 v246, 0, v66, s[74:75]
	v_cndmask_b32_e64 v247, 0, v67, s[74:75]
	v_cndmask_b32_e64 v64, 0, v64, s[72:73]
	v_cndmask_b32_e64 v65, 0, v65, s[72:73]
	v_cndmask_b32_e64 v66, 0, v66, s[72:73]
	v_cndmask_b32_e64 v67, 0, v67, s[72:73]
	v_add_f32_e32 v100, v100, v244
	v_add_f32_e32 v101, v101, v245
	v_add_f32_e32 v102, v102, v246
	v_add_f32_e32 v103, v103, v247
	v_add_f32_dpp v80, v64, v80 row_ror:8 row_mask:0xf bank_mask:0xf
	v_add_f32_dpp v81, v65, v81 row_ror:8 row_mask:0xf bank_mask:0xf
	v_add_f32_dpp v82, v66, v82 row_ror:8 row_mask:0xf bank_mask:0xf
	v_add_f32_dpp v83, v67, v83 row_ror:8 row_mask:0xf bank_mask:0xf
	v_cndmask_b32_e64 v244, 0, v104, s[74:75]
	v_cndmask_b32_e64 v245, 0, v105, s[74:75]
	v_cndmask_b32_e64 v246, 0, v106, s[74:75]
	v_cndmask_b32_e64 v247, 0, v107, s[74:75]
	v_cndmask_b32_e64 v104, 0, v104, s[72:73]
	v_cndmask_b32_e64 v105, 0, v105, s[72:73]
	v_cndmask_b32_e64 v106, 0, v106, s[72:73]
	v_cndmask_b32_e64 v107, 0, v107, s[72:73]
	v_add_f32_e32 v96, v96, v244
	v_add_f32_e32 v97, v97, v245
	v_add_f32_e32 v98, v98, v246
	v_add_f32_e32 v99, v99, v247
	v_add_f32_dpp v72, v104, v72 row_ror:8 row_mask:0xf bank_mask:0xf
	v_add_f32_dpp v73, v105, v73 row_ror:8 row_mask:0xf bank_mask:0xf
	v_add_f32_dpp v74, v106, v74 row_ror:8 row_mask:0xf bank_mask:0xf
	v_add_f32_dpp v75, v107, v75 row_ror:8 row_mask:0xf bank_mask:0xf
	v_cndmask_b32_e64 v244, 0, v234, s[74:75]
	v_cndmask_b32_e64 v245, 0, v235, s[74:75]
	v_cndmask_b32_e64 v246, 0, v236, s[74:75]
	v_cndmask_b32_e64 v247, 0, v237, s[74:75]
	v_cndmask_b32_e64 v234, 0, v234, s[72:73]
	v_cndmask_b32_e64 v235, 0, v235, s[72:73]
	v_cndmask_b32_e64 v236, 0, v236, s[72:73]
	v_cndmask_b32_e64 v237, 0, v237, s[72:73]
	v_add_f32_e32 v88, v88, v244
	v_add_f32_e32 v89, v89, v245
	v_add_f32_e32 v90, v90, v246
	v_add_f32_e32 v91, v91, v247
	v_add_f32_dpp v60, v234, v60 row_ror:8 row_mask:0xf bank_mask:0xf
	v_add_f32_dpp v61, v235, v61 row_ror:8 row_mask:0xf bank_mask:0xf
	v_add_f32_dpp v62, v236, v62 row_ror:8 row_mask:0xf bank_mask:0xf
	v_add_f32_dpp v63, v237, v63 row_ror:8 row_mask:0xf bank_mask:0xf
	v_cndmask_b32_e64 v244, 0, v238, s[74:75]
	v_cndmask_b32_e64 v245, 0, v239, s[74:75]
	v_cndmask_b32_e64 v246, 0, v240, s[74:75]
	v_cndmask_b32_e64 v247, 0, v241, s[74:75]
	v_cndmask_b32_e64 v238, 0, v238, s[72:73]
	v_cndmask_b32_e64 v239, 0, v239, s[72:73]
	v_cndmask_b32_e64 v240, 0, v240, s[72:73]
	v_cndmask_b32_e64 v241, 0, v241, s[72:73]
	v_add_f32_e32 v84, v84, v244
	v_add_f32_e32 v85, v85, v245
	v_add_f32_e32 v86, v86, v246
	v_add_f32_e32 v87, v87, v247
	v_add_f32_dpp v36, v238, v36 row_ror:8 row_mask:0xf bank_mask:0xf
	v_add_f32_dpp v37, v239, v37 row_ror:8 row_mask:0xf bank_mask:0xf
	v_add_f32_dpp v38, v240, v38 row_ror:8 row_mask:0xf bank_mask:0xf
	v_add_f32_dpp v39, v241, v39 row_ror:8 row_mask:0xf bank_mask:0xf
	s_branch .LBB0_793
.LBB0_855:
	v_mfma_f32_16x16x32_bf16 v[72:75], v[56:59], v[104:107], v[72:75]
	s_add_i32 s13, s13, 1
	s_addk_i32 s2, 0x100
	s_add_i32 s12, s12, 4
	v_mfma_f32_16x16x32_bf16 v[80:83], v[92:95], v[104:107], v[80:83]
	v_add_u32_e32 v108, 0xffffff00, v108
	s_cmpk_lg_i32 s2, 0x1000
	v_mfma_f32_16x16x32_bf16 v[84:87], v[52:55], v[104:107], v[84:87]
	v_mfma_f32_16x16x32_bf16 v[88:91], v[76:79], v[104:107], v[88:91]
	s_waitcnt lgkmcnt(1)
	v_mfma_f32_16x16x32_bf16 v[96:99], v[48:51], v[104:107], v[96:99]
	v_mfma_f32_16x16x32_bf16 v[100:103], v[68:71], v[104:107], v[100:103]
	s_cbranch_scc0 .Lhy2H_entry
